# grid barrier: waiting workgroups poll the chip-wide generation word directly (per-XCD republication hop removed)
# baseline (speedup 1.0000x reference)
.LBB0_320:
	s_or_b64 exec, exec, s[4:5]
	v_cvt_f32_u32_e32 v5, v3
	s_waitcnt vmcnt(0)
	v_readfirstlane_b32 s2, v4
	v_sub_u32_e32 v4, 0, v3
	v_rcp_iflag_f32_e32 v5, v5
	v_add_u32_e32 v6, s2, v2
	v_mul_f32_e32 v5, 0x4f7ffffe, v5
	v_cvt_u32_f32_e32 v5, v5
	v_mul_lo_u32 v2, v4, v5
	v_mul_hi_u32 v2, v5, v2
	v_add_u32_e32 v2, v5, v2
	v_mul_hi_u32 v2, v6, v2
	v_mul_lo_u32 v4, v2, v3
	v_sub_u32_e32 v4, v6, v4
	v_add_u32_e32 v5, 1, v2
	v_sub_u32_e32 v7, v4, v3
	v_cmp_ge_u32_e32 vcc, v4, v3
	s_nop 1
	v_cndmask_b32_e32 v2, v2, v5, vcc
	v_cndmask_b32_e32 v4, v4, v7, vcc
	v_add_u32_e32 v5, 1, v2
	v_cmp_ge_u32_e32 vcc, v4, v3
	v_add_u32_e32 v4, 1, v6
	s_nop 0
	v_cndmask_b32_e32 v2, v2, v5, vcc
	v_mul_lo_u32 v5, v3, v2
	v_add_u32_e32 v3, v5, v3
	v_cmp_ne_u32_e32 vcc, v4, v3
	s_and_saveexec_b64 s[4:5], vcc
	s_xor_b64 s[4:5], exec, s[4:5]
	s_cbranch_execz .LBB0_334
	s_add_u32 s12, s60, 0x3500
	s_addc_u32 s13, s61, 0
	s_waitcnt lgkmcnt(0)
	s_nop 3
	global_load_dword v0, v1, s[12:13] sc1
	s_waitcnt vmcnt(0)
	v_cmp_eq_u32_e32 vcc, v0, v2
	s_and_saveexec_b64 s[36:37], vcc
	s_cbranch_execz .LBB0_333
	s_mov_b32 s2, 1
	s_mov_b64 s[38:39], 0
	s_branch .LBB0_324

.LBB0_326:
	s_add_u32 s12, s60, 0x3500
	s_addc_u32 s13, s61, 0
	s_add_i32 s2, s2, 1
	s_mov_b64 s[46:47], -1
	s_nop 2
	global_load_dword v0, v1, s[12:13] sc1
	s_waitcnt vmcnt(0)
	v_cmp_ne_u32_e32 vcc, v0, v2
	s_orn2_b64 s[44:45], vcc, exec
	s_branch .LBB0_323

.LBB0_351:
	s_or_b64 exec, exec, s[36:37]
	s_mov_b64 s[36:37], exec
	v_mbcnt_lo_u32_b32 v0, s36, 0
	v_mbcnt_hi_u32_b32 v0, s37, v0
	v_cmp_eq_u32_e32 vcc, 0, v0
	s_waitcnt vmcnt(0)
	buffer_inv sc1
	s_and_saveexec_b64 s[38:39], vcc
	s_cbranch_execz .LBB0_353
	s_bcnt1_i32_b64 s2, s[36:37]
	v_readlane_b32 s12, v253, 50
	v_mov_b32_e32 v0, s2
	v_readlane_b32 s13, v253, 51
	s_nop 4
	s_nop 0

.LBB0_546:
	s_or_b64 exec, exec, s[4:5]
	v_cvt_f32_u32_e32 v5, v3
	s_waitcnt vmcnt(0)
	v_readfirstlane_b32 s2, v4
	v_sub_u32_e32 v4, 0, v3
	v_rcp_iflag_f32_e32 v5, v5
	v_add_u32_e32 v6, s2, v0
	v_mul_f32_e32 v5, 0x4f7ffffe, v5
	v_cvt_u32_f32_e32 v5, v5
	v_mul_lo_u32 v0, v4, v5
	v_mul_hi_u32 v0, v5, v0
	v_add_u32_e32 v0, v5, v0
	v_mul_hi_u32 v0, v6, v0
	v_mul_lo_u32 v4, v0, v3
	v_sub_u32_e32 v4, v6, v4
	v_add_u32_e32 v5, 1, v0
	v_cmp_ge_u32_e32 vcc, v4, v3
	s_nop 1
	v_cndmask_b32_e32 v0, v0, v5, vcc
	v_sub_u32_e32 v5, v4, v3
	v_cndmask_b32_e32 v4, v4, v5, vcc
	v_add_u32_e32 v5, 1, v0
	v_cmp_ge_u32_e32 vcc, v4, v3
	v_add_u32_e32 v4, 1, v6
	s_nop 0
	v_cndmask_b32_e32 v0, v0, v5, vcc
	v_mul_lo_u32 v5, v3, v0
	v_add_u32_e32 v3, v5, v3
	v_cmp_ne_u32_e32 vcc, v4, v3
	s_and_saveexec_b64 s[4:5], vcc
	s_xor_b64 s[4:5], exec, s[4:5]
	s_cbranch_execz .LBB0_560
	s_add_u32 s6, s60, 0x3500
	s_addc_u32 s7, s61, 0
	s_waitcnt lgkmcnt(0)
	s_nop 3
	global_load_dword v2, v1, s[6:7] sc1
	s_waitcnt vmcnt(0)
	v_cmp_eq_u32_e32 vcc, v2, v0
	s_and_saveexec_b64 s[6:7], vcc
	s_cbranch_execz .LBB0_559
	s_mov_b32 s2, 1
	s_mov_b64 s[36:37], 0
	s_branch .LBB0_550

.LBB0_552:
	s_add_u32 s12, s60, 0x3500
	s_addc_u32 s13, s61, 0
	s_add_i32 s2, s2, 1
	s_mov_b64 s[44:45], -1
	s_nop 2
	global_load_dword v2, v1, s[12:13] sc1
	s_waitcnt vmcnt(0)
	v_cmp_ne_u32_e32 vcc, v2, v0
	s_orn2_b64 s[42:43], vcc, exec
	s_branch .LBB0_549

.LBB0_577:
	s_or_b64 exec, exec, s[4:5]
	s_mov_b64 s[4:5], exec
	v_mbcnt_lo_u32_b32 v0, s4, 0
	v_mbcnt_hi_u32_b32 v0, s5, v0
	v_cmp_eq_u32_e32 vcc, 0, v0
	s_waitcnt vmcnt(0)
	buffer_inv sc1
	s_and_saveexec_b64 s[6:7], vcc
	s_cbranch_execz .LBB0_579
	s_bcnt1_i32_b64 s2, s[4:5]
	v_readlane_b32 s4, v253, 50
	v_mov_b32_e32 v0, s2
	v_readlane_b32 s5, v253, 51
	s_nop 4
	s_nop 0

.LBB0_1066:
	s_or_b64 exec, exec, s[6:7]
	s_mov_b64 s[6:7], exec
	v_mbcnt_lo_u32_b32 v0, s6, 0
	v_mbcnt_hi_u32_b32 v0, s7, v0
	v_cmp_eq_u32_e32 vcc, 0, v0
	s_waitcnt vmcnt(0)
	buffer_inv sc1
	s_and_saveexec_b64 s[36:37], vcc
	s_cbranch_execz .LBB0_139
	s_bcnt1_i32_b64 s2, s[6:7]
	v_readlane_b32 s6, v253, 50
	v_mov_b32_e32 v0, s2
	v_readlane_b32 s7, v253, 51
	s_nop 4
	s_nop 0
	s_branch .LBB0_139

.LBB0_1233:
	s_or_b64 exec, exec, s[6:7]
	s_mov_b64 s[6:7], exec
	v_mbcnt_lo_u32_b32 v0, s6, 0
	v_mbcnt_hi_u32_b32 v0, s7, v0
	v_cmp_eq_u32_e32 vcc, 0, v0
	s_waitcnt vmcnt(0)
	buffer_inv sc1
	s_and_saveexec_b64 s[36:37], vcc
	s_cbranch_execz .LBB0_1235
	s_bcnt1_i32_b64 s2, s[6:7]
	v_readlane_b32 s6, v253, 50
	v_mov_b32_e32 v0, s2
	v_readlane_b32 s7, v253, 51
	s_nop 4
	s_nop 0

.LBB0_1500:
	s_bcnt1_i32_b64 s2, s[4:5]
	v_readlane_b32 s4, v253, 50
	v_mov_b32_e32 v0, s2
	v_readlane_b32 s5, v253, 51
	s_nop 4
	s_nop 0
	s_getpc_b64 s[98:99]
